# v18 + windowed attention loops: next K/V tile written to LDS at the top of the iteration (target buffer is already free), so only the barrier remains at the tail
# speedup vs baseline: 1.0239x; 1.0006x over previous
; #define LAS __attribute__((address_space(3)))
; DI s16x4 vtr(const LAS unsigned char* p) { return __builtin_bit_cast(s16x4, __builtin_amdgcn_ds_read_tr16_b64_v4i16((LAS s16x4*)p)); }
; template <int DQK, bool WIN>
; DI void attn_run(int wv, const bf16_t* Qrow0, int qs, const bf16_t* Kb, int ks, const bf16_t* Vb, int vs,
;                  int kt0, int kt1, int qpos0, int window, LAS unsigned char* lds, f32x16 (&o)[2], float& m_out, float& l_out) {
;     ...
;     for (int kt = kt0; kt < kt1; ++kt) {
;         const int buf = (kt - kt0) & 1;
;         const bool more = (kt + 1 < kt1);
;         if (kt + 2 < kt1) { const size_t ko = (size_t)(kt + 2) * 64 * ks, vo = (size_t)(kt + 2) * 64 * vs;
;             nk0 = gld16(kg0 + ko); if (k2) nk1 = gld16(kg1 + ko); nv = gld16(vg + vo); }
;         bool need = true;
;         if (WIN) need = (64 * kt + 63 >= qpos0 - window) && (64 * kt <= qpos0 + 31 + window);
;         if (need) {
;             const LAS unsigned char* base = lds + buf * BUF;
;             bf16x8 kf0[NDS], kf1[NDS];
; #pragma unroll
;             for (int ds = 0; ds < NDS; ++ds) {
;                 kf0[ds] = *(const LAS bf16x8*)(base + kfo + ds * 32);
;                 kf1[ds] = *(const LAS bf16x8*)(base + kfo + 32 * KP + ds * 32);
;             }
;             __builtin_amdgcn_s_setprio(1);
;             f32x16 p0 = __builtin_amdgcn_mfma_f32_32x32x16_bf16(kf0[0], q[0], negm, 0, 0, 0);
;             f32x16 p1 = __builtin_amdgcn_mfma_f32_32x32x16_bf16(kf1[0], q[0], negm, 0, 0, 0);
; #pragma unroll
;             for (int ds = 1; ds < NDS; ++ds) {
;                 p0 = __builtin_amdgcn_mfma_f32_32x32x16_bf16(kf0[ds], q[ds], p0, 0, 0, 0);
;                 p1 = __builtin_amdgcn_mfma_f32_32x32x16_bf16(kf1[ds], q[ds], p1, 0, 0, 0);
;             }
;             __builtin_amdgcn_s_setprio(0);
;             s16x4 vlo[4][2], vhi[4][2];
; #pragma unroll
;             for (int k4 = 0; k4 < 4; ++k4)
; #pragma unroll
;                 for (int db = 0; db < 2; ++db) {
;                     vlo[k4][db] = vtr(base + vfo + (16 * k4) * VP + 64 * db);
;                     vhi[k4][db] = vtr(base + vfo + (16 * k4 + 8) * VP + 64 * db);
;                 }
;     ...
;         if (more) { LAS unsigned char* nb = lds + (buf ^ 1) * BUF;
;             *(LAS u32x4*)(nb + kl0) = rk0; if (k2) *(LAS u32x4*)(nb + kl1) = rk1; *(LAS u32x4*)(nb + vl) = rv; }
.LBB0_1246:
	s_add_i32 s26, s44, s13
	s_sub_i32 vcc_hi, s26, 64
	s_add_i32 m0, s34, 31
	s_cmp_ge_i32 vcc_hi, m0
	s_cselect_b32 m0, 1, 0
	s_sub_i32 vcc_lo, s35, 0x5e
	s_cmp_le_i32 vcc_hi, vcc_lo
	s_cselect_b32 vcc_lo, 1, 0
	s_and_b32 m0, m0, vcc_lo
	s_and_b32 s15, s12, 1
	s_cmp_ge_i32 s14, s31
	s_cbranch_scc1 .Lew_d_skip
	s_xor_b32 vcc_lo, s15, 1
	s_mul_i32 vcc_lo, vcc_lo, 0x5400
	v_add_u32_e32 v218, vcc_lo, v153
	v_add_u32_e32 v219, vcc_lo, v136
	ds_write_b128 v218, v[96:99]
	ds_write_b128 v219, v[100:103] offset:9216
.Lew_d_skip:
	s_sub_i32 s28, s26, 64
	s_add_i32 s26, s26, -1
	s_cmp_ge_i32 s26, s34
	s_cselect_b64 s[26:27], -1, 0
	s_cmp_le_i32 s28, s35
	s_cselect_b64 s[28:29], -1, 0
	s_and_b64 s[26:27], s[26:27], s[28:29]
	s_andn2_b64 vcc, exec, s[26:27]
	s_cbranch_vccnz .LBB0_1255
	s_mul_i32 s26, s15, 0x5400
	s_add_i32 s28, s26, 0
	v_add3_u32 v52, s28, v154, v144
	ds_read_b128 v[48:51], v52
	ds_read_b128 v[112:115], v52 offset:32
	ds_read_b128 v[116:119], v52 offset:4608
	ds_read_b128 v[120:123], v52 offset:4640
	ds_read_b128 v[124:127], v52 offset:64
	ds_read_b128 v[146:149], v52 offset:96
	ds_read_b128 v[162:165], v52 offset:4672
	ds_read_b128 v[166:169], v52 offset:4704
	s_xor_b64 s[26:27], s[24:25], -1
	s_setprio 1
	s_waitcnt lgkmcnt(0)
	v_mfma_f32_32x32x16_bf16 v[64:79], v[48:51], v[80:83], v[32:47]
	s_waitcnt lgkmcnt(5)
	v_mfma_f32_32x32x16_bf16 v[48:63], v[116:119], v[80:83], v[32:47]
	s_setprio 0
	v_mfma_f32_32x32x16_bf16 v[64:79], v[112:115], v[84:87], v[64:79]
	v_add_u32_e32 v112, s28, v156
	s_waitcnt lgkmcnt(4)
	v_mfma_f32_32x32x16_bf16 v[48:63], v[120:123], v[84:87], v[48:63]
	v_add3_u32 v152, v112, v155, v157
	ds_read_b64_tr_b16 v[132:133], v152 offset:9216
	ds_read_b64_tr_b16 v[134:135], v152 offset:10752
	ds_read_b64_tr_b16 v[130:131], v152 offset:10816
	ds_read_b64_tr_b16 v[128:129], v152 offset:9280
	s_waitcnt lgkmcnt(7)
	v_mfma_f32_32x32x16_bf16 v[64:79], v[124:127], v[88:91], v[64:79]
	ds_read_b64_tr_b16 v[124:125], v152 offset:12288
	ds_read_b64_tr_b16 v[126:127], v152 offset:13824
	ds_read_b64_tr_b16 v[122:123], v152 offset:13888
	ds_read_b64_tr_b16 v[120:121], v152 offset:12352
	ds_read_b64_tr_b16 v[116:117], v152 offset:15360
	ds_read_b64_tr_b16 v[118:119], v152 offset:16896
	ds_read_b64_tr_b16 v[114:115], v152 offset:16960
	ds_read_b64_tr_b16 v[112:113], v152 offset:15424
	s_waitcnt lgkmcnt(13)
	v_mfma_f32_32x32x16_bf16 v[48:63], v[162:165], v[88:91], v[48:63]
	v_mfma_f32_32x32x16_bf16 v[64:79], v[146:149], v[92:95], v[64:79]
	s_waitcnt lgkmcnt(12)
	v_mfma_f32_32x32x16_bf16 v[48:63], v[166:169], v[92:95], v[48:63]
	s_cmp_eq_u32 m0, 1
	s_cbranch_scc0 .Lwd_slow
	s_nop 7
	v_mov_b32_e32 v142, v64
	s_nop 0
	v_mov_b32_e32 v64, v48
	v_mov_b32_e32 v143, v65
	v_mov_b32_e32 v65, v49
	v_mov_b32_e32 v146, v66
	v_mov_b32_e32 v66, v50
	v_mov_b32_e32 v147, v67
	v_mov_b32_e32 v67, v51
	v_mov_b32_e32 v148, v68
	v_mov_b32_e32 v68, v52
	v_mov_b32_e32 v149, v69
	v_mov_b32_e32 v69, v53
	v_mov_b32_e32 v150, v70
	v_mov_b32_e32 v70, v54
	v_mov_b32_e32 v151, v71
	v_mov_b32_e32 v71, v55
	s_branch .Lwd_join

; #define LAS __attribute__((address_space(3)))
; #define ATTN_BAR() asm volatile("s_waitcnt lgkmcnt(0)\n\ts_barrier" ::: "memory")
; template <int DQK, bool WIN>
; DI void attn_run(int wv, const bf16_t* Qrow0, int qs, const bf16_t* Kb, int ks, const bf16_t* Vb, int vs,
;                  int kt0, int kt1, int qpos0, int window, LAS unsigned char* lds, f32x16 (&o)[2], float& m_out, float& l_out) {
;     ...
;         if (more) { LAS unsigned char* nb = lds + (buf ^ 1) * BUF;
;             *(LAS u32x4*)(nb + kl0) = rk0; if (k2) *(LAS u32x4*)(nb + kl1) = rk1; *(LAS u32x4*)(nb + vl) = rv; }
;         ATTN_BAR();
;         rk0 = nk0; rk1 = nk1; rv = nv;
;     }
.LBB0_1255:
.LBB0_1257:
	s_add_i32 s12, s12, 1
	s_waitcnt lgkmcnt(0)
	s_barrier
	s_add_i32 s14, s30, s12
	s_add_i32 s13, s13, 64
	s_add_i32 s14, s14, -1
	v_add_u32_e32 v158, 64, v158
	v_subrev_u32_e32 v159, 64, v159
	v_lshl_add_u64 v[138:139], v[138:139], 0, s[94:95]
	s_cmp_lt_i32 s14, s31
	v_lshl_add_u64 v[140:141], v[140:141], 0, s[94:95]
	s_cbranch_scc0 .LBB0_1261
	s_waitcnt vmcnt(0)
	v_mov_b64_e32 v[96:97], v[108:109]
	s_waitcnt vmcnt(0)
	v_mov_b64_e32 v[100:101], v[104:105]
	v_mov_b64_e32 v[98:99], v[110:111]
	v_mov_b64_e32 v[102:103], v[106:107]
	s_add_i32 s14, s30, s12
	s_add_i32 s15, s14, 1
	s_cmp_ge_i32 s15, s31
	s_cbranch_scc0 .LBB0_1245
	s_branch .LBB0_1246

; #define LAS __attribute__((address_space(3)))
; DI s16x4 vtr(const LAS unsigned char* p) { return __builtin_bit_cast(s16x4, __builtin_amdgcn_ds_read_tr16_b64_v4i16((LAS s16x4*)p)); }
; template <int DQK, bool WIN>
; DI void attn_run(int wv, const bf16_t* Qrow0, int qs, const bf16_t* Kb, int ks, const bf16_t* Vb, int vs,
;                  int kt0, int kt1, int qpos0, int window, LAS unsigned char* lds, f32x16 (&o)[2], float& m_out, float& l_out) {
;     ...
;     for (int kt = kt0; kt < kt1; ++kt) {
;         const int buf = (kt - kt0) & 1;
;         const bool more = (kt + 1 < kt1);
;         if (kt + 2 < kt1) { const size_t ko = (size_t)(kt + 2) * 64 * ks, vo = (size_t)(kt + 2) * 64 * vs;
;             nk0 = gld16(kg0 + ko); if (k2) nk1 = gld16(kg1 + ko); nv = gld16(vg + vo); }
;         bool need = true;
;         if (WIN) need = (64 * kt + 63 >= qpos0 - window) && (64 * kt <= qpos0 + 31 + window);
;         if (need) {
;             const LAS unsigned char* base = lds + buf * BUF;
;             bf16x8 kf0[NDS], kf1[NDS];
; #pragma unroll
;             for (int ds = 0; ds < NDS; ++ds) {
;                 kf0[ds] = *(const LAS bf16x8*)(base + kfo + ds * 32);
;                 kf1[ds] = *(const LAS bf16x8*)(base + kfo + 32 * KP + ds * 32);
;             }
;             __builtin_amdgcn_s_setprio(1);
;             f32x16 p0 = __builtin_amdgcn_mfma_f32_32x32x16_bf16(kf0[0], q[0], negm, 0, 0, 0);
;             f32x16 p1 = __builtin_amdgcn_mfma_f32_32x32x16_bf16(kf1[0], q[0], negm, 0, 0, 0);
; #pragma unroll
;             for (int ds = 1; ds < NDS; ++ds) {
;                 p0 = __builtin_amdgcn_mfma_f32_32x32x16_bf16(kf0[ds], q[ds], p0, 0, 0, 0);
;                 p1 = __builtin_amdgcn_mfma_f32_32x32x16_bf16(kf1[ds], q[ds], p1, 0, 0, 0);
;             }
;             __builtin_amdgcn_s_setprio(0);
;             s16x4 vlo[4][2], vhi[4][2];
; #pragma unroll
;             for (int k4 = 0; k4 < 4; ++k4)
; #pragma unroll
;                 for (int db = 0; db < 2; ++db) {
;                     vlo[k4][db] = vtr(base + vfo + (16 * k4) * VP + 64 * db);
;                     vhi[k4][db] = vtr(base + vfo + (16 * k4 + 8) * VP + 64 * db);
;                 }
;     ...
;         if (more) { LAS unsigned char* nb = lds + (buf ^ 1) * BUF;
;             *(LAS u32x4*)(nb + kl0) = rk0; if (k2) *(LAS u32x4*)(nb + kl1) = rk1; *(LAS u32x4*)(nb + vl) = rv; }
.LBB0_1272:
	s_add_i32 s15, s68, -2
	s_add_i32 s36, s12, s13
	s_add_i32 m0, s75, 31
	s_cmp_ge_i32 s36, m0
	s_cselect_b32 m0, 1, 0
	s_sub_i32 vcc_lo, s14, 0x5e
	s_cmp_le_i32 s36, vcc_lo
	s_cselect_b32 vcc_lo, 1, 0
	s_and_b32 m0, m0, vcc_lo
	s_and_b32 s15, s15, 1
	s_add_i32 vcc_lo, s68, -1
	s_cmp_ge_u32 vcc_lo, s17
	s_cbranch_scc1 .Lew_c_skip
	s_xor_b32 vcc_lo, s15, 1
	s_mul_i32 vcc_lo, vcc_lo, 0x5400
	v_add_u32_e32 v218, vcc_lo, v153
	v_add_u32_e32 v219, vcc_lo, v136
	ds_write_b128 v218, v[96:99]
	ds_write_b128 v219, v[100:103] offset:9216
.Lew_c_skip:
	s_add_i32 s30, s36, 63
	s_cmp_ge_i32 s30, s75
	s_cselect_b64 s[30:31], -1, 0
	s_cmp_le_u32 s36, s14
	s_cselect_b64 s[36:37], -1, 0
	s_and_b64 s[30:31], s[30:31], s[36:37]
	s_andn2_b64 vcc, exec, s[30:31]
	s_cbranch_vccnz .LBB0_1281
	s_mul_i32 s30, s15, 0x5400
	s_add_i32 s36, s30, 0
	v_add3_u32 v52, s36, v154, v144
	ds_read_b128 v[48:51], v52
	ds_read_b128 v[112:115], v52 offset:32
	ds_read_b128 v[116:119], v52 offset:4608
	ds_read_b128 v[120:123], v52 offset:4640
	ds_read_b128 v[124:127], v52 offset:64
	ds_read_b128 v[146:149], v52 offset:96
	ds_read_b128 v[162:165], v52 offset:4672
	ds_read_b128 v[166:169], v52 offset:4704
	s_xor_b64 s[30:31], s[28:29], -1
	s_setprio 1
	s_waitcnt lgkmcnt(0)
	v_mfma_f32_32x32x16_bf16 v[64:79], v[48:51], v[80:83], v[32:47]
	v_mfma_f32_32x32x16_bf16 v[48:63], v[116:119], v[80:83], v[32:47]
	s_setprio 0
	v_mfma_f32_32x32x16_bf16 v[64:79], v[112:115], v[84:87], v[64:79]
	v_add_u32_e32 v112, s36, v156
	v_add3_u32 v152, v112, v155, v157
	v_mfma_f32_32x32x16_bf16 v[48:63], v[120:123], v[84:87], v[48:63]
	v_mfma_f32_32x32x16_bf16 v[64:79], v[124:127], v[88:91], v[64:79]
	ds_read_b64_tr_b16 v[132:133], v152 offset:9216
	ds_read_b64_tr_b16 v[134:135], v152 offset:10752
	ds_read_b64_tr_b16 v[130:131], v152 offset:10816
	ds_read_b64_tr_b16 v[128:129], v152 offset:9280
	ds_read_b64_tr_b16 v[124:125], v152 offset:12288
	ds_read_b64_tr_b16 v[126:127], v152 offset:13824
	ds_read_b64_tr_b16 v[122:123], v152 offset:13888
	ds_read_b64_tr_b16 v[120:121], v152 offset:12352
	ds_read_b64_tr_b16 v[116:117], v152 offset:15360
	ds_read_b64_tr_b16 v[118:119], v152 offset:16896
	ds_read_b64_tr_b16 v[114:115], v152 offset:16960
	ds_read_b64_tr_b16 v[112:113], v152 offset:15424
	v_mfma_f32_32x32x16_bf16 v[48:63], v[162:165], v[88:91], v[48:63]
	v_mfma_f32_32x32x16_bf16 v[64:79], v[146:149], v[92:95], v[64:79]
	v_mfma_f32_32x32x16_bf16 v[48:63], v[166:169], v[92:95], v[48:63]
	s_cmp_eq_u32 m0, 1
	s_cbranch_scc0 .Lwc_slow
	s_nop 8
	v_mov_b32_e32 v142, v64
	v_mov_b32_e32 v64, v48
	v_mov_b32_e32 v143, v65
	v_mov_b32_e32 v65, v49
	v_mov_b32_e32 v146, v66
	v_mov_b32_e32 v66, v50
	v_mov_b32_e32 v147, v67
	v_mov_b32_e32 v67, v51
	v_mov_b32_e32 v148, v68
	v_mov_b32_e32 v68, v52
	v_mov_b32_e32 v149, v69
	v_mov_b32_e32 v69, v53
	v_mov_b32_e32 v150, v70
	v_mov_b32_e32 v70, v54
	v_mov_b32_e32 v151, v71
	v_mov_b32_e32 v71, v55
	s_branch .Lwc_join

; #define LAS __attribute__((address_space(3)))
; #define ATTN_BAR() asm volatile("s_waitcnt lgkmcnt(0)\n\ts_barrier" ::: "memory")
; template <int DQK, bool WIN>
; DI void attn_run(int wv, const bf16_t* Qrow0, int qs, const bf16_t* Kb, int ks, const bf16_t* Vb, int vs,
;                  int kt0, int kt1, int qpos0, int window, LAS unsigned char* lds, f32x16 (&o)[2], float& m_out, float& l_out) {
;     ...
;         if (more) { LAS unsigned char* nb = lds + (buf ^ 1) * BUF;
;             *(LAS u32x4*)(nb + kl0) = rk0; if (k2) *(LAS u32x4*)(nb + kl1) = rk1; *(LAS u32x4*)(nb + vl) = rv; }
;         ATTN_BAR();
;         rk0 = nk0; rk1 = nk1; rv = nv;
;     }
.LBB0_1281:
	s_add_i32 s30, s68, -1
.LBB0_1283:
	s_waitcnt lgkmcnt(0)
	s_barrier
	s_add_i32 s13, s13, 64
	s_add_i32 s68, s68, 1
	v_add_u32_e32 v158, 64, v158
	v_subrev_u32_e32 v159, 64, v159
	v_lshl_add_u64 v[138:139], v[138:139], 0, s[94:95]
	s_cmp_lt_u32 s30, s17
	v_lshl_add_u64 v[140:141], v[140:141], 0, s[94:95]
	s_cbranch_scc0 .LBB0_1286
	s_waitcnt vmcnt(0)
	v_mov_b64_e32 v[96:97], v[108:109]
	v_mov_b64_e32 v[100:101], v[104:105]
	v_mov_b64_e32 v[98:99], v[110:111]
	v_mov_b64_e32 v[102:103], v[106:107]
	s_cmp_ge_u32 s68, s17
	s_cbranch_scc0 .LBB0_1271
	s_branch .LBB0_1272
